# waves 0-3 raised once at kernel entry and never reset (all phases), GEMM flips deleted
# baseline (speedup 1.0000x reference)
; #define LAS __attribute__((address_space(3)))
; template <bool COOP>
; __global__ void __launch_bounds__(512, 2) mega(Args A) {
;     extern __shared__ __attribute__((aligned(16))) unsigned char smem[];
;     LAS unsigned char* lds = (LAS unsigned char*)smem;
;     unsigned char* ws = A.ws; const int G = gridDim.x, c = blockIdx.x;
;     float* ss = (float*)(ws + WS_SS); float* ssp = (float*)(ws + WS_SSP); u16* xb = (u16*)(ws + WS_XB); u16* proj = (u16*)(ws + WS_PROJ); float* dt = (float*)(ws + WS_DT);
;     ...
;     XcdBarrier xbar; xbar.bar = (unsigned*)(ws + WS_BAR); xbar.x = 0; xbar.st = (volatile LAS unsigned*)(lds + 131072);
;     if (COOP) { if (threadIdx.x < 4) ((LAS unsigned*)(lds + 131072))[threadIdx.x] = 0u;
;         if (blockIdx.x == 0 && threadIdx.x < 51) { const int i_ = threadIdx.x;
;             const int w_ = i_ < 16 ? XB_XCNT(i_) : (i_ < 32 ? XB_XSUB(i_ - 16) : (i_ < 48 ? XB_XGEN(i_ - 32) : (i_ == 48 ? XB_TOP : (i_ == 49 ? XB_TOPGEN : XB_TMO))));
;             __hip_atomic_store((unsigned*)(ws + WS_BAR) + w_, 0u, __ATOMIC_RELAXED, __HIP_MEMORY_SCOPE_AGENT); }
;         __syncthreads(); }
_Z4megaILb1EEv4Args:
	s_load_dwordx2 s[74:75], s[0:1], 0xc0
	s_mov_b32 s93, s2
	s_add_u32 s2, s0, 0xd8
	s_addc_u32 s3, s1, 0
	v_and_b32_e32 v152, 0x3ff, v0
	v_readfirstlane_b32 s98, v152
	s_nop 3
	s_cmp_lt_u32 s98, 0x100
	s_cbranch_scc0 .Lps_skip
	s_setprio 1
.Lps_skip:
	v_writelane_b32 v251, s2, 0
	v_cmp_gt_u32_e32 vcc, 4, v152
	s_nop 0
	v_writelane_b32 v251, s3, 1
	s_and_saveexec_b64 s[2:3], vcc
	v_lshl_add_u32 v1, v152, 2, 0
	v_add_u32_e32 v1, 0x20000, v1
	v_mov_b32_e32 v2, 0
	ds_write_b32 v1, v2
	s_or_b64 exec, exec, s[2:3]
	s_load_dwordx2 s[40:41], s[0:1], 0xc8
	s_load_dword s92, s[0:1], 0xd8
	s_waitcnt lgkmcnt(0)
	s_add_u32 s2, s74, 0x3c3c0000
	s_addc_u32 s3, s75, 0
	v_writelane_b32 v251, s2, 2
	s_cmp_eq_u32 s93, 0
	v_cmp_gt_u32_e32 vcc, 51, v152
	v_writelane_b32 v251, s3, 3
	s_cselect_b64 s[2:3], -1, 0
	s_and_b64 s[4:5], s[2:3], vcc
	s_and_saveexec_b64 s[2:3], s[4:5]
	s_cbranch_execz .LBB0_16
	v_cmp_lt_u32_e32 vcc, 15, v152
	s_and_saveexec_b64 s[4:5], vcc
	s_xor_b64 s[4:5], exec, s[4:5]
	s_cbranch_execz .LBB0_13
	v_cmp_lt_u32_e32 vcc, 31, v152
	s_and_saveexec_b64 s[6:7], vcc
	s_xor_b64 s[6:7], exec, s[6:7]
	s_cbranch_execz .LBB0_10
	v_cmp_lt_u32_e32 vcc, 47, v152
	s_and_saveexec_b64 s[8:9], vcc
	s_xor_b64 s[8:9], exec, s[8:9]
	v_mov_b32_e32 v1, 0x80
	v_mov_b32_e32 v2, 0xd40
	v_cmp_eq_u32_e32 vcc, 49, v152
	s_nop 1
	v_cndmask_b32_e32 v1, v1, v2, vcc
	v_mov_b32_e32 v2, 0xd00
	v_cmp_ne_u32_e32 vcc, 48, v152
	s_nop 1
	v_cndmask_b32_e32 v2, v2, v1, vcc
	s_andn2_saveexec_b64 s[8:9], s[8:9]
	v_mov_b32_e32 v1, 0x100
	v_lshl_add_u32 v2, v152, 6, v1
	s_or_b64 exec, exec, s[8:9]
